# MLA attention: cross-half row-max exchange via v_permlane32_swap instead of ds_bpermute
# speedup vs baseline: 1.1274x; 1.0009x over previous
; DI float fexp2(float x) { return __builtin_amdgcn_exp2f(x); }
;     ...
;             float mt = fmaxf(s[j][0], s[j][1]);
; #pragma unroll
;             for (int i = 2; i < 16; ++i) mt = fmaxf(mt, s[j][i]);
;             mt = fmaxf(mt, __shfl_xor(mt, 32));
;             if (MODE == 1) mt *= c2;
;             const float cand = fmaxf(mrun, mt);
;             if (__any(cand > mrun + 8.f)) {
;               const float alpha = fexp2(mrun - cand);
;               mrun = cand; lsum *= alpha;
; #pragma unroll
;               for (int i = 0; i < 16; ++i) { oacc[0][i] *= alpha; oacc[1][i] *= alpha; }
;             }
;             const float nm = -mrun;
; #pragma unroll
.LBB0_830:
	s_or_b64 exec, exec, s[8:9]
	v_add_f32_e32 v128, v201, v209
	v_add_f32_e32 v128, v211, v128
	v_max_f32_e32 v129, v33, v33
	v_max_f32_e32 v130, v32, v32
	v_add_f32_e32 v128, v212, v128
	v_max_f32_e32 v129, v130, v129
	v_add_f32_e32 v128, v213, v128
	v_max3_f32 v129, v129, v34, v35
	v_add_f32_e32 v128, v214, v128
	v_max3_f32 v129, v129, v36, v37
	v_add_f32_e32 v128, v215, v128
	v_max3_f32 v129, v129, v38, v39
	v_add_f32_e32 v128, v216, v128
	v_max3_f32 v129, v129, v40, v41
	v_add_f32_e32 v128, v217, v128
	v_max3_f32 v129, v129, v42, v43
	v_add_f32_e32 v128, v218, v128
	v_max3_f32 v129, v129, v44, v45
	v_add_f32_e32 v128, v219, v128
	v_max3_f32 v130, v129, v46, v47
	v_add_f32_e32 v128, v220, v128
	v_mov_b32_e32 v131, v130
	v_mov_b32_e32 v230, v130
	s_nop 1
	v_permlane32_swap_b32_e32 v131, v230
	v_max_f32_e32 v131, v131, v230
	v_add_f32_e32 v128, v221, v128
	v_add_f32_e32 v128, v203, v128
	v_add_f32_e32 v128, v207, v128
	v_add_f32_e32 v128, v208, v128
	v_add_f32_e32 v129, v210, v128
	s_waitcnt lgkmcnt(0)
	v_max_f32_e32 v128, v131, v131
	v_max_f32_e32 v128, v130, v128
	v_mul_f32_e32 v128, 0x3e16c73f, v128
	v_max_f32_e32 v130, v202, v202
	v_max_f32_e32 v130, v130, v128
	v_add_f32_e32 v128, 0x41000000, v202
	v_cmp_gt_f32_e32 vcc, v130, v128
	s_cbranch_vccz .LBB0_853
	v_sub_f32_e32 v128, v202, v130
	v_exp_f32_e32 v128, v128
	v_mov_b32_e32 v202, v130
	v_mul_f32_e32 v129, v129, v128
	v_pk_mul_f32 v[30:31], v[30:31], v[128:129] op_sel_hi:[1,0]
	v_pk_mul_f32 v[28:29], v[28:29], v[128:129] op_sel_hi:[1,0]
	v_pk_mul_f32 v[26:27], v[26:27], v[128:129] op_sel_hi:[1,0]
	v_pk_mul_f32 v[24:25], v[24:25], v[128:129] op_sel_hi:[1,0]
	v_pk_mul_f32 v[22:23], v[22:23], v[128:129] op_sel_hi:[1,0]
	v_pk_mul_f32 v[20:21], v[20:21], v[128:129] op_sel_hi:[1,0]
	v_pk_mul_f32 v[18:19], v[18:19], v[128:129] op_sel_hi:[1,0]
	v_pk_mul_f32 v[16:17], v[16:17], v[128:129] op_sel_hi:[1,0]
	v_pk_mul_f32 v[14:15], v[14:15], v[128:129] op_sel_hi:[1,0]
	v_pk_mul_f32 v[12:13], v[12:13], v[128:129] op_sel_hi:[1,0]
	v_pk_mul_f32 v[10:11], v[10:11], v[128:129] op_sel_hi:[1,0]
	v_pk_mul_f32 v[8:9], v[8:9], v[128:129] op_sel_hi:[1,0]
	v_pk_mul_f32 v[6:7], v[6:7], v[128:129] op_sel_hi:[1,0]
	v_pk_mul_f32 v[4:5], v[4:5], v[128:129] op_sel_hi:[1,0]
	v_pk_mul_f32 v[2:3], v[2:3], v[128:129] op_sel_hi:[1,0]
	v_pk_mul_f32 v[0:1], v[0:1], v[128:129] op_sel_hi:[1,0]
	v_xor_b32_e32 v128, 0x80000000, v130

; DI float fexp2(float x) { return __builtin_amdgcn_exp2f(x); }
;     ...
;             float mt = fmaxf(s[j][0], s[j][1]);
; #pragma unroll
;             for (int i = 2; i < 16; ++i) mt = fmaxf(mt, s[j][i]);
;             mt = fmaxf(mt, __shfl_xor(mt, 32));
;             if (MODE == 1) mt *= c2;
;             const float cand = fmaxf(mrun, mt);
;             if (__any(cand > mrun + 8.f)) {
;               const float alpha = fexp2(mrun - cand);
;               mrun = cand; lsum *= alpha;
; #pragma unroll
;               for (int i = 0; i < 16; ++i) { oacc[0][i] *= alpha; oacc[1][i] *= alpha; }
;             }
;             const float nm = -mrun;
; #pragma unroll
.LBB0_837:
	s_or_b64 exec, exec, s[8:9]
	v_max_f32_e32 v202, v49, v49
	v_max_f32_e32 v205, v48, v48
	v_max_f32_e32 v202, v205, v202
	v_max3_f32 v202, v202, v50, v51
	v_max3_f32 v202, v202, v52, v53
	v_max3_f32 v202, v202, v54, v55
	v_and_b32_e32 v208, 64, v182
	v_max3_f32 v202, v202, v56, v57
	v_xor_b32_e32 v205, 32, v182
	v_add_u32_e32 v208, 64, v208
	v_max3_f32 v202, v202, v58, v59
	v_cmp_lt_i32_e32 vcc, v205, v208
	v_max3_f32 v202, v202, v60, v61
	v_max3_f32 v202, v202, v62, v63
	v_cndmask_b32_e32 v205, v182, v205, vcc
	v_lshlrev_b32_e32 v205, 2, v205
	v_mov_b32_e32 v208, v202
	v_mov_b32_e32 v230, v202
	s_nop 1
	v_permlane32_swap_b32_e32 v208, v230
	v_max_f32_e32 v208, v208, v230
	s_waitcnt lgkmcnt(0)
	v_max_f32_e32 v208, v208, v208
	v_max_f32_e32 v202, v202, v208
	v_mul_f32_e32 v202, 0x3e16c73f, v202
	v_max_f32_e32 v208, v203, v203
	v_max_f32_e32 v202, v208, v202
	v_add_f32_e32 v208, 0x41000000, v203
	v_cmp_gt_f32_e32 vcc, v202, v208
	s_cbranch_vccz .LBB0_839
	v_sub_f32_e32 v203, v203, v202
	v_exp_f32_e32 v208, v203
	s_nop 0
	v_mul_f32_e32 v201, v201, v208
	v_pk_mul_f32 v[30:31], v[30:31], v[208:209] op_sel_hi:[1,0]
	v_pk_mul_f32 v[28:29], v[28:29], v[208:209] op_sel_hi:[1,0]
	v_pk_mul_f32 v[26:27], v[26:27], v[208:209] op_sel_hi:[1,0]
	v_pk_mul_f32 v[24:25], v[24:25], v[208:209] op_sel_hi:[1,0]
	v_pk_mul_f32 v[22:23], v[22:23], v[208:209] op_sel_hi:[1,0]
	v_pk_mul_f32 v[20:21], v[20:21], v[208:209] op_sel_hi:[1,0]
	v_pk_mul_f32 v[18:19], v[18:19], v[208:209] op_sel_hi:[1,0]
	v_pk_mul_f32 v[16:17], v[16:17], v[208:209] op_sel_hi:[1,0]
	v_pk_mul_f32 v[14:15], v[14:15], v[208:209] op_sel_hi:[1,0]
	v_pk_mul_f32 v[12:13], v[12:13], v[208:209] op_sel_hi:[1,0]
	v_pk_mul_f32 v[10:11], v[10:11], v[208:209] op_sel_hi:[1,0]
	v_pk_mul_f32 v[8:9], v[8:9], v[208:209] op_sel_hi:[1,0]
	v_pk_mul_f32 v[6:7], v[6:7], v[208:209] op_sel_hi:[1,0]
	v_pk_mul_f32 v[4:5], v[4:5], v[208:209] op_sel_hi:[1,0]
	v_pk_mul_f32 v[2:3], v[2:3], v[208:209] op_sel_hi:[1,0]
	v_pk_mul_f32 v[0:1], v[0:1], v[208:209] op_sel_hi:[1,0]
	s_branch .LBB0_840

; DI float fexp2(float x) { return __builtin_amdgcn_exp2f(x); }
;     ...
;             float mt = fmaxf(s[j][0], s[j][1]);
; #pragma unroll
;             for (int i = 2; i < 16; ++i) mt = fmaxf(mt, s[j][i]);
;             mt = fmaxf(mt, __shfl_xor(mt, 32));
;             if (MODE == 1) mt *= c2;
;             const float cand = fmaxf(mrun, mt);
;             if (__any(cand > mrun + 8.f)) {
;               const float alpha = fexp2(mrun - cand);
;               mrun = cand; lsum *= alpha;
; #pragma unroll
;               for (int i = 0; i < 16; ++i) { oacc[0][i] *= alpha; oacc[1][i] *= alpha; }
;             }
;             const float nm = -mrun;
; #pragma unroll
.LBB0_842:
	s_or_b64 exec, exec, s[8:9]
	v_add_f32_e32 v128, v201, v210
	v_add_f32_e32 v128, v212, v128
	v_max_f32_e32 v129, v33, v33
	v_max_f32_e32 v130, v32, v32
	v_add_f32_e32 v128, v213, v128
	v_max_f32_e32 v129, v130, v129
	v_add_f32_e32 v128, v214, v128
	v_max3_f32 v129, v129, v34, v35
	v_add_f32_e32 v128, v215, v128
	v_max3_f32 v129, v129, v36, v37
	v_add_f32_e32 v128, v216, v128
	v_max3_f32 v129, v129, v38, v39
	v_add_f32_e32 v128, v217, v128
	v_max3_f32 v129, v129, v40, v41
	v_add_f32_e32 v128, v218, v128
	v_max3_f32 v129, v129, v42, v43
	v_add_f32_e32 v128, v219, v128
	v_max3_f32 v129, v129, v44, v45
	v_add_f32_e32 v128, v220, v128
	v_max3_f32 v130, v129, v46, v47
	v_add_f32_e32 v128, v221, v128
	v_mov_b32_e32 v131, v130
	v_mov_b32_e32 v230, v130
	s_nop 1
	v_permlane32_swap_b32_e32 v131, v230
	v_max_f32_e32 v131, v131, v230
	v_add_f32_e32 v128, v222, v128
	v_add_f32_e32 v128, v203, v128
	v_add_f32_e32 v128, v208, v128
	v_add_f32_e32 v128, v209, v128
	v_add_f32_e32 v129, v211, v128
	s_waitcnt lgkmcnt(0)
	v_max_f32_e32 v128, v131, v131
	v_max_f32_e32 v128, v130, v128
	v_mul_f32_e32 v128, 0x3e16c73f, v128
	v_max_f32_e32 v130, v202, v202
	v_max_f32_e32 v130, v130, v128
	v_add_f32_e32 v128, 0x41000000, v202
	v_cmp_gt_f32_e32 vcc, v130, v128
	s_cbranch_vccz .LBB0_844
	v_sub_f32_e32 v128, v202, v130
	v_exp_f32_e32 v128, v128
	v_mov_b32_e32 v202, v130
	v_mul_f32_e32 v129, v129, v128
	v_pk_mul_f32 v[30:31], v[30:31], v[128:129] op_sel_hi:[1,0]
	v_pk_mul_f32 v[28:29], v[28:29], v[128:129] op_sel_hi:[1,0]
	v_pk_mul_f32 v[26:27], v[26:27], v[128:129] op_sel_hi:[1,0]
	v_pk_mul_f32 v[24:25], v[24:25], v[128:129] op_sel_hi:[1,0]
	v_pk_mul_f32 v[22:23], v[22:23], v[128:129] op_sel_hi:[1,0]
	v_pk_mul_f32 v[20:21], v[20:21], v[128:129] op_sel_hi:[1,0]
	v_pk_mul_f32 v[18:19], v[18:19], v[128:129] op_sel_hi:[1,0]
	v_pk_mul_f32 v[16:17], v[16:17], v[128:129] op_sel_hi:[1,0]
	v_pk_mul_f32 v[14:15], v[14:15], v[128:129] op_sel_hi:[1,0]
	v_pk_mul_f32 v[12:13], v[12:13], v[128:129] op_sel_hi:[1,0]
	v_pk_mul_f32 v[10:11], v[10:11], v[128:129] op_sel_hi:[1,0]
	v_pk_mul_f32 v[8:9], v[8:9], v[128:129] op_sel_hi:[1,0]
	v_pk_mul_f32 v[6:7], v[6:7], v[128:129] op_sel_hi:[1,0]
	v_pk_mul_f32 v[4:5], v[4:5], v[128:129] op_sel_hi:[1,0]
	v_pk_mul_f32 v[2:3], v[2:3], v[128:129] op_sel_hi:[1,0]
	v_pk_mul_f32 v[0:1], v[0:1], v[128:129] op_sel_hi:[1,0]
	v_xor_b32_e32 v128, 0x80000000, v130
	s_branch .LBB0_845

; DI float fexp2(float x) { return __builtin_amdgcn_exp2f(x); }
;     ...
;             float mt = fmaxf(s[j][0], s[j][1]);
; #pragma unroll
;             for (int i = 2; i < 16; ++i) mt = fmaxf(mt, s[j][i]);
;             mt = fmaxf(mt, __shfl_xor(mt, 32));
;             if (MODE == 1) mt *= c2;
;             const float cand = fmaxf(mrun, mt);
;             if (__any(cand > mrun + 8.f)) {
;               const float alpha = fexp2(mrun - cand);
;               mrun = cand; lsum *= alpha;
; #pragma unroll
;               for (int i = 0; i < 16; ++i) { oacc[0][i] *= alpha; oacc[1][i] *= alpha; }
;             }
;             const float nm = -mrun;
; #pragma unroll
.LBB0_850:
	s_or_b64 exec, exec, s[8:9]
	v_max_f32_e32 v202, v49, v49
	v_max_f32_e32 v204, v48, v48
	v_max_f32_e32 v202, v204, v202
	v_max3_f32 v202, v202, v50, v51
	v_max3_f32 v202, v202, v52, v53
	v_max3_f32 v202, v202, v54, v55
	v_and_b32_e32 v207, 64, v182
	v_max3_f32 v202, v202, v56, v57
	v_xor_b32_e32 v204, 32, v182
	v_add_u32_e32 v207, 64, v207
	v_max3_f32 v202, v202, v58, v59
	v_cmp_lt_i32_e32 vcc, v204, v207
	v_max3_f32 v202, v202, v60, v61
	v_max3_f32 v202, v202, v62, v63
	v_cndmask_b32_e32 v204, v182, v204, vcc
	v_lshlrev_b32_e32 v204, 2, v204
	v_mov_b32_e32 v207, v202
	v_mov_b32_e32 v230, v202
	s_nop 1
	v_permlane32_swap_b32_e32 v207, v230
	v_max_f32_e32 v207, v207, v230
	s_waitcnt lgkmcnt(0)
	v_max_f32_e32 v207, v207, v207
	v_max_f32_e32 v202, v202, v207
	v_mul_f32_e32 v202, 0x3e16c73f, v202
	v_max_f32_e32 v207, v203, v203
	v_max_f32_e32 v202, v207, v202
	v_add_f32_e32 v207, 0x41000000, v203
	v_cmp_gt_f32_e32 vcc, v202, v207
	s_cbranch_vccz .LBB0_854
	v_sub_f32_e32 v203, v203, v202
	v_exp_f32_e32 v208, v203
	s_nop 0
	v_mul_f32_e32 v201, v201, v208
	v_pk_mul_f32 v[30:31], v[30:31], v[208:209] op_sel_hi:[1,0]
	v_pk_mul_f32 v[28:29], v[28:29], v[208:209] op_sel_hi:[1,0]
	v_pk_mul_f32 v[26:27], v[26:27], v[208:209] op_sel_hi:[1,0]
	v_pk_mul_f32 v[24:25], v[24:25], v[208:209] op_sel_hi:[1,0]
	v_pk_mul_f32 v[22:23], v[22:23], v[208:209] op_sel_hi:[1,0]
	v_pk_mul_f32 v[20:21], v[20:21], v[208:209] op_sel_hi:[1,0]
	v_pk_mul_f32 v[18:19], v[18:19], v[208:209] op_sel_hi:[1,0]
	v_pk_mul_f32 v[16:17], v[16:17], v[208:209] op_sel_hi:[1,0]
	v_pk_mul_f32 v[14:15], v[14:15], v[208:209] op_sel_hi:[1,0]
	v_pk_mul_f32 v[12:13], v[12:13], v[208:209] op_sel_hi:[1,0]
	v_pk_mul_f32 v[10:11], v[10:11], v[208:209] op_sel_hi:[1,0]
	v_pk_mul_f32 v[8:9], v[8:9], v[208:209] op_sel_hi:[1,0]
	v_pk_mul_f32 v[6:7], v[6:7], v[208:209] op_sel_hi:[1,0]
	v_pk_mul_f32 v[4:5], v[4:5], v[208:209] op_sel_hi:[1,0]
	v_pk_mul_f32 v[2:3], v[2:3], v[208:209] op_sel_hi:[1,0]
	v_pk_mul_f32 v[0:1], v[0:1], v[208:209] op_sel_hi:[1,0]
	s_branch .LBB0_855
